# attention loop: softmax exp/pack/row-sum software-pipelined into PV MFMA gaps; loop control before the barrier; negm as SrcC; DMA issued inside PV
# speedup vs baseline: 1.0547x; 1.0271x over previous
; #define SBAR() __builtin_amdgcn_sched_barrier(0)
; __device__ __forceinline__ s16x4 vtr(lds_cptr p){ return __builtin_bit_cast(s16x4,__builtin_amdgcn_ds_read_tr16_b64_v4i16((__attribute__((address_space(3))) v4i16_t*)p)); }
; template<int THRL> __device__ __forceinline__ void attn_unit(int qb,const bf16*Q,const bf16*__restrict__ K,const bf16*__restrict__ V,bf16*O,char*shm){
;     ...
;     bf16x8 kf[8]; kload8(kf,kp0+c0*SLOTB);
;     SBAR();
;     f32x16 C0,C1;
;     {
;       C0=__builtin_amdgcn_mfma_f32_32x32x16_bf16(kf[0],qr[0],negm,0,0,0); C1=__builtin_amdgcn_mfma_f32_32x32x16_bf16(kf[1],qr[0],negm,0,0,0);
;       C0=__builtin_amdgcn_mfma_f32_32x32x16_bf16(kf[2],qr[1],C0,0,0,0);   C1=__builtin_amdgcn_mfma_f32_32x32x16_bf16(kf[3],qr[1],C1,0,0,0);
;       C0=__builtin_amdgcn_mfma_f32_32x32x16_bf16(kf[4],qr[2],C0,0,0,0);   C1=__builtin_amdgcn_mfma_f32_32x32x16_bf16(kf[5],qr[2],C1,0,0,0);
;       C0=__builtin_amdgcn_mfma_f32_32x32x16_bf16(kf[6],qr[3],C0,0,0,0);   C1=__builtin_amdgcn_mfma_f32_32x32x16_bf16(kf[7],qr[3],C1,0,0,0); }
;     SBAR();
;     const lds_cptr vp_=vp0+c0*VSLOTB; s16x4 vl_[8],vh_[8];
;     #pragma unroll
;     for(int k2=0;k2<2;++k2)
;       #pragma unroll
;       for(int d_=0;d_<4;++d_){ vl_[d_*2+k2]=vtr(vp_+(d_*4096+k2*1024)); vh_[d_*2+k2]=vtr(vp_+(d_*4096+k2*1024+512)); }
;     SBAR();
;     { const int jb_=t-(NT-4); if(jb_>=0)cmask(C0,C1,jb_,qrel,hi); }
.LBB0_366:
.Lattn_top:
	v_lshl_add_u32 v80, s34, 13, v189
	ds_read_b128 v[96:99], v80
	ds_read_b128 v[128:131], v80 offset:512
	ds_read_b128 v[100:103], v80 offset:2048
	ds_read_b128 v[132:135], v80 offset:2560
	ds_read_b128 v[104:107], v80 offset:4096
	ds_read_b128 v[144:147], v80 offset:4608
	ds_read_b128 v[108:111], v80 offset:6144
	ds_read_b128 v[194:197], v80 offset:6656
	s_waitcnt lgkmcnt(7)
	v_mfma_f32_32x32x16_bf16 v[80:95], v[96:99], v[112:115], v[64:79]
	s_waitcnt lgkmcnt(5)
	v_mfma_f32_32x32x16_bf16 v[80:95], v[100:103], v[116:119], v[80:95]
	s_waitcnt lgkmcnt(3)
	v_mfma_f32_32x32x16_bf16 v[80:95], v[104:107], v[120:123], v[80:95]
	s_waitcnt lgkmcnt(1)
	v_mfma_f32_32x32x16_bf16 v[80:95], v[108:111], v[124:127], v[80:95]
	s_lshl_b32 s14, s34, 14
	v_add_u32_e32 v193, s14, v190
	v_mfma_f32_32x32x16_bf16 v[96:111], v[128:131], v[112:115], v[64:79]
	ds_read_b64_tr_b16 v[156:157], v193 offset:24576
	ds_read_b64_tr_b16 v[158:159], v193 offset:25088
	ds_read_b64_tr_b16 v[140:141], v193 offset:25600
	ds_read_b64_tr_b16 v[142:143], v193 offset:26112
	ds_read_b64_tr_b16 v[152:153], v193 offset:28672
	ds_read_b64_tr_b16 v[154:155], v193 offset:29184
	ds_read_b64_tr_b16 v[136:137], v193 offset:29696
	ds_read_b64_tr_b16 v[138:139], v193 offset:30208
	v_mfma_f32_32x32x16_bf16 v[96:111], v[132:135], v[116:119], v[96:111]
	v_mfma_f32_32x32x16_bf16 v[96:111], v[144:147], v[120:123], v[96:111]
	ds_read_b64_tr_b16 v[148:149], v193 offset:32768
	ds_read_b64_tr_b16 v[150:151], v193 offset:33280
	ds_read_b64_tr_b16 v[132:133], v193 offset:33792
	ds_read_b64_tr_b16 v[134:135], v193 offset:34304
	ds_read_b64_tr_b16 v[144:145], v193 offset:36864
	ds_read_b64_tr_b16 v[146:147], v193 offset:37376
	ds_read_b64_tr_b16 v[128:129], v193 offset:37888
	ds_read_b64_tr_b16 v[130:131], v193 offset:38400
	s_waitcnt lgkmcnt(14)
	v_mfma_f32_32x32x16_bf16 v[96:111], v[194:197], v[124:127], v[96:111]
	s_add_i32 s14, s28, s31
	s_cmp_lt_i32 s14, -4
	s_cbranch_scc1 .LBB0_368
	v_subrev_u32_e32 v163, 27, v192
	v_subrev_u32_e32 v162, 59, v192
	v_cmp_le_i32_e32 vcc, v163, v188
	s_nop 5
	v_cndmask_b32_e32 v96, v229, v96, vcc
	v_cmp_lt_i32_e32 vcc, v162, v188
	s_nop 1
	v_cndmask_b32_e32 v81, v229, v81, vcc
	v_cmp_le_i32_e32 vcc, v162, v188
	v_subrev_u32_e32 v162, 26, v192
	s_nop 0
	v_cndmask_b32_e32 v80, v229, v80, vcc
	v_cmp_le_i32_e32 vcc, v162, v188
	v_subrev_u32_e32 v162, 57, v192
	s_nop 0
	v_cndmask_b32_e32 v97, v229, v97, vcc
	v_cmp_le_i32_e32 vcc, v162, v188
	v_subrev_u32_e32 v162, 25, v192
	s_nop 0
	v_cndmask_b32_e32 v82, v229, v82, vcc
	v_cmp_le_i32_e32 vcc, v162, v188
	v_subrev_u32_e32 v162, 56, v192
	s_nop 0
	v_cndmask_b32_e32 v98, v229, v98, vcc
	v_cmp_le_i32_e32 vcc, v162, v188
	v_subrev_u32_e32 v162, 24, v192
	s_nop 0
	v_cndmask_b32_e32 v83, v229, v83, vcc
	v_cmp_le_i32_e32 vcc, v162, v188
	v_subrev_u32_e32 v162, 51, v192
	s_nop 0
	v_cndmask_b32_e32 v99, v229, v99, vcc
	v_cmp_le_i32_e32 vcc, v162, v188
	v_subrev_u32_e32 v162, 19, v192
	s_nop 0
	v_cndmask_b32_e32 v84, v229, v84, vcc
	v_cmp_le_i32_e32 vcc, v162, v188
	v_subrev_u32_e32 v162, 50, v192
	s_nop 0
	v_cndmask_b32_e32 v100, v229, v100, vcc
	v_cmp_le_i32_e32 vcc, v162, v188
	v_subrev_u32_e32 v162, 18, v192
	s_nop 0
	v_cndmask_b32_e32 v85, v229, v85, vcc
	v_cmp_le_i32_e32 vcc, v162, v188
	v_subrev_u32_e32 v162, 49, v192
	s_nop 0
	v_cndmask_b32_e32 v101, v229, v101, vcc
	v_cmp_le_i32_e32 vcc, v162, v188
	v_subrev_u32_e32 v162, 17, v192
	s_nop 0
	v_cndmask_b32_e32 v86, v229, v86, vcc
	v_cmp_le_i32_e32 vcc, v162, v188
	v_subrev_u32_e32 v162, 48, v192
	s_nop 0
	v_cndmask_b32_e32 v102, v229, v102, vcc
	v_cmp_le_i32_e32 vcc, v162, v188
	v_add_u32_e32 v162, -16, v192
	s_nop 0
	v_cndmask_b32_e32 v87, v229, v87, vcc
	v_cmp_le_i32_e32 vcc, v162, v188
	v_subrev_u32_e32 v162, 43, v192
	s_nop 0
	v_cndmask_b32_e32 v103, v229, v103, vcc
	v_cmp_le_i32_e32 vcc, v162, v188
	v_add_u32_e32 v162, -11, v192
	s_nop 0
	v_cndmask_b32_e32 v88, v229, v88, vcc
	v_cmp_le_i32_e32 vcc, v162, v188
	v_subrev_u32_e32 v162, 42, v192
	s_nop 0
	v_cndmask_b32_e32 v104, v229, v104, vcc
	v_cmp_le_i32_e32 vcc, v162, v188
	v_add_u32_e32 v162, -10, v192
	s_nop 0
	v_cndmask_b32_e32 v89, v229, v89, vcc
	v_cmp_le_i32_e32 vcc, v162, v188
	v_subrev_u32_e32 v162, 41, v192
	s_nop 0
	v_cndmask_b32_e32 v105, v229, v105, vcc
	v_cmp_le_i32_e32 vcc, v162, v188
	v_add_u32_e32 v162, -9, v192
	s_nop 0
	v_cndmask_b32_e32 v90, v229, v90, vcc
	v_cmp_le_i32_e32 vcc, v162, v188
	v_subrev_u32_e32 v162, 40, v192
	s_nop 0
	v_cndmask_b32_e32 v106, v229, v106, vcc
	v_cmp_le_i32_e32 vcc, v162, v188
	v_add_u32_e32 v162, -8, v192
	s_nop 0
	v_cndmask_b32_e32 v91, v229, v91, vcc
	v_cmp_le_i32_e32 vcc, v162, v188
	v_subrev_u32_e32 v162, 35, v192
	s_nop 0
	v_cndmask_b32_e32 v107, v229, v107, vcc
	v_cmp_le_i32_e32 vcc, v162, v188
	v_add_u32_e32 v162, -3, v192
	s_nop 0
	v_cndmask_b32_e32 v92, v229, v92, vcc
	v_cmp_le_i32_e32 vcc, v162, v188
	v_subrev_u32_e32 v162, 34, v192
	s_nop 0
	v_cndmask_b32_e32 v108, v229, v108, vcc
	v_cmp_le_i32_e32 vcc, v162, v188
	v_add_u32_e32 v162, -2, v192
	s_nop 0
	v_cndmask_b32_e32 v93, v229, v93, vcc
	v_cmp_le_i32_e32 vcc, v162, v188
	v_subrev_u32_e32 v162, 33, v192
	s_nop 0
	v_cndmask_b32_e32 v109, v229, v109, vcc
	v_cmp_le_i32_e32 vcc, v162, v188
	v_add_u32_e32 v162, -1, v192
	s_nop 0
	v_cndmask_b32_e32 v94, v229, v94, vcc
	v_cmp_le_i32_e32 vcc, v162, v188
	v_subrev_u32_e32 v162, 32, v192
	s_nop 0
	v_cndmask_b32_e32 v110, v229, v110, vcc
	v_cmp_le_i32_e32 vcc, v162, v188
	s_nop 1
	v_cndmask_b32_e32 v95, v229, v95, vcc
	v_cmp_le_i32_e32 vcc, v192, v188
	s_nop 1
	v_cndmask_b32_e32 v111, v229, v111, vcc
; __device__ __forceinline__ int crow(int r,int hi){return (r&3)+8*(r>>2)+4*hi;}
;   #define MX3(a,b,c) __builtin_fmaxf(__builtin_fmaxf((a),(b)),(c))
; template<int THRL> __device__ __forceinline__ void attn_unit(int qb,const bf16*Q,const bf16*__restrict__ K,const bf16*__restrict__ V,bf16*O,char*shm){
;     ...
;     float a=MX3(C0[0],C0[1],C1[0]),b=MX3(C0[2],C0[3],C1[1]); a=MX3(a,C1[2],C1[3]);
;     #pragma unroll
;     for(int r=4;r<16;r+=4){a=MX3(a,C0[r],C0[r+1]);b=MX3(b,C0[r+2],C0[r+3]);a=MX3(a,C1[r],C1[r+1]);b=MX3(b,C1[r+2],C1[r+3]);}
;     float rm=__builtin_fmaxf(a,b); { auto rr=__builtin_amdgcn_permlane32_swap(__float_as_uint(rm),__float_as_uint(rm),false,false); rm=__builtin_fmaxf(__uint_as_float(rr[0]),__uint_as_float(rr[1])); }
;     if(t==0 || __any(rm>(float)THRL)){
;       const float dl=(t==0)?rm:__builtin_fmaxf(rm,0.f); mhat+=dl;
;       #pragma unroll
;       for(int r=0;r<16;++r){C0[r]-=dl;C1[r]-=dl;}
;       #pragma unroll
;       for(int r=0;r<16;++r)negm[r]=-mhat;
;       if(t!=0){ const float f=__builtin_amdgcn_exp2f(-dl); l_reg*=f; if(hi==0)wsf[r32]=f; asm volatile("s_waitcnt lgkmcnt(0)":::"memory");
;         #pragma unroll
;         for(int d_=0;d_<4;++d_)
;           #pragma unroll
;           for(int r=0;r<16;++r)o[d_][r]*=wsf[crow(r,hi)]; } }
.LBB0_368:
	v_max3_f32 v162, v80, v81, v82
	v_max3_f32 v163, v83, v84, v85
	v_max3_f32 v162, v162, v86, v87
	v_max3_f32 v163, v163, v88, v89
	v_max3_f32 v162, v162, v90, v91
	v_max3_f32 v163, v163, v92, v93
	v_max3_f32 v162, v162, v94, v95
	s_nop 1
	v_max3_f32 v163, v163, v96, v97
	v_max3_f32 v162, v162, v98, v99
	v_max3_f32 v163, v163, v100, v101
	v_max3_f32 v162, v162, v102, v103
	v_max3_f32 v163, v163, v104, v105
	v_max3_f32 v162, v162, v106, v107
	v_max3_f32 v163, v163, v108, v109
	v_max3_f32 v162, v162, v110, v111
	v_max_f32_e32 v162, v162, v163
	v_mov_b32_e32 v163, v162
	s_nop 1
	v_permlane32_swap_b32_e32 v162, v163
	v_max_f32_e32 v184, v162, v163
	s_mov_b32 s14, 0x41000000
	v_cmp_lt_f32_e32 vcc, s14, v184
	s_cbranch_vccz .LBB0_372
	v_max_f32_e32 v64, v184, v184
	v_max_f32_e32 v64, 0, v64
	v_exp_f32_e64 v65, -v64
	s_and_saveexec_b64 s[14:15], s[4:5]
	ds_write_b32 v191, v65
	s_or_b64 exec, exec, s[14:15]
	s_waitcnt lgkmcnt(0)
	v_pk_add_f32 v[80:81], v[80:81], v[64:65] op_sel_hi:[1,0] neg_lo:[0,1] neg_hi:[0,1]
	v_pk_add_f32 v[96:97], v[96:97], v[64:65] op_sel_hi:[1,0] neg_lo:[0,1] neg_hi:[0,1]
	v_pk_add_f32 v[82:83], v[82:83], v[64:65] op_sel_hi:[1,0] neg_lo:[0,1] neg_hi:[0,1]
	v_pk_add_f32 v[98:99], v[98:99], v[64:65] op_sel_hi:[1,0] neg_lo:[0,1] neg_hi:[0,1]
	v_pk_add_f32 v[84:85], v[84:85], v[64:65] op_sel_hi:[1,0] neg_lo:[0,1] neg_hi:[0,1]
	v_pk_add_f32 v[100:101], v[100:101], v[64:65] op_sel_hi:[1,0] neg_lo:[0,1] neg_hi:[0,1]
	v_pk_add_f32 v[86:87], v[86:87], v[64:65] op_sel_hi:[1,0] neg_lo:[0,1] neg_hi:[0,1]
	v_pk_add_f32 v[102:103], v[102:103], v[64:65] op_sel_hi:[1,0] neg_lo:[0,1] neg_hi:[0,1]
	v_pk_add_f32 v[88:89], v[88:89], v[64:65] op_sel_hi:[1,0] neg_lo:[0,1] neg_hi:[0,1]
	v_pk_add_f32 v[104:105], v[104:105], v[64:65] op_sel_hi:[1,0] neg_lo:[0,1] neg_hi:[0,1]
	v_pk_add_f32 v[90:91], v[90:91], v[64:65] op_sel_hi:[1,0] neg_lo:[0,1] neg_hi:[0,1]
	v_pk_add_f32 v[106:107], v[106:107], v[64:65] op_sel_hi:[1,0] neg_lo:[0,1] neg_hi:[0,1]
	v_pk_add_f32 v[92:93], v[92:93], v[64:65] op_sel_hi:[1,0] neg_lo:[0,1] neg_hi:[0,1]
	v_pk_add_f32 v[108:109], v[108:109], v[64:65] op_sel_hi:[1,0] neg_lo:[0,1] neg_hi:[0,1]
	v_pk_add_f32 v[94:95], v[94:95], v[64:65] op_sel_hi:[1,0] neg_lo:[0,1] neg_hi:[0,1]
	v_pk_add_f32 v[110:111], v[110:111], v[64:65] op_sel_hi:[1,0] neg_lo:[0,1] neg_hi:[0,1]
	v_pk_add_f32 v[184:185], v[178:179], v[64:65]
	v_pk_mul_f32 v[76:77], v[178:179], v[64:65]
	ds_read_b128 v[64:67], v160 offset:64
	ds_read_b128 v[68:71], v160 offset:96
	ds_read_b128 v[72:75], v160
	ds_read_b128 v[194:197], v160 offset:32
	v_mov_b32_e32 v185, v77
	v_pk_add_f32 v[78:79], v[184:185], 0 neg_lo:[1,1] neg_hi:[1,1]
	s_waitcnt lgkmcnt(2)
	v_pk_mul_f32 v[60:61], v[60:61], v[68:69]
	v_pk_mul_f32 v[56:57], v[56:57], v[64:65]
	s_waitcnt lgkmcnt(0)
	v_pk_mul_f32 v[52:53], v[52:53], v[194:195]
	v_pk_mul_f32 v[62:63], v[62:63], v[70:71]
	v_pk_mul_f32 v[58:59], v[58:59], v[66:67]
	v_pk_mul_f32 v[54:55], v[54:55], v[196:197]
	v_pk_mul_f32 v[50:51], v[50:51], v[74:75]
	v_pk_mul_f32 v[48:49], v[48:49], v[72:73]
	v_pk_mul_f32 v[44:45], v[44:45], v[68:69]
	v_pk_mul_f32 v[40:41], v[40:41], v[64:65]
	v_pk_mul_f32 v[36:37], v[36:37], v[194:195]
	v_pk_mul_f32 v[46:47], v[46:47], v[70:71]
	v_pk_mul_f32 v[42:43], v[42:43], v[66:67]
	v_pk_mul_f32 v[38:39], v[38:39], v[196:197]
	v_pk_mul_f32 v[34:35], v[34:35], v[74:75]
	v_pk_mul_f32 v[32:33], v[32:33], v[72:73]
	v_pk_mul_f32 v[28:29], v[28:29], v[68:69]
	v_pk_mul_f32 v[24:25], v[24:25], v[64:65]
	v_pk_mul_f32 v[20:21], v[20:21], v[194:195]
	v_pk_mul_f32 v[30:31], v[30:31], v[70:71]
	v_pk_mul_f32 v[26:27], v[26:27], v[66:67]
	v_pk_mul_f32 v[22:23], v[22:23], v[196:197]
	v_pk_mul_f32 v[18:19], v[18:19], v[74:75]
	v_pk_mul_f32 v[16:17], v[16:17], v[72:73]
	v_pk_mul_f32 v[12:13], v[12:13], v[68:69]
	v_pk_mul_f32 v[8:9], v[8:9], v[64:65]
	v_pk_mul_f32 v[4:5], v[4:5], v[194:195]
	v_pk_mul_f32 v[14:15], v[14:15], v[70:71]
	v_pk_mul_f32 v[10:11], v[10:11], v[66:67]
	v_pk_mul_f32 v[6:7], v[6:7], v[196:197]
	v_pk_mul_f32 v[2:3], v[2:3], v[74:75]
	v_pk_mul_f32 v[0:1], v[0:1], v[72:73]
	v_mov_b32_e32 v79, v78
	v_mov_b32_e32 v77, v78
	v_mov_b32_e32 v76, v78
	v_mov_b32_e32 v75, v78
	v_mov_b32_e32 v74, v78
	v_mov_b32_e32 v73, v78
	v_mov_b32_e32 v72, v78
	v_mov_b32_e32 v71, v78
	v_mov_b32_e32 v70, v78
	v_mov_b32_e32 v69, v78
	v_mov_b32_e32 v68, v78
	v_mov_b32_e32 v67, v78
	v_mov_b32_e32 v66, v78
	v_mov_b32_e32 v65, v78
	v_mov_b32_e32 v64, v78
	v_mov_b64_e32 v[178:179], v[184:185]
; #define SBAR() __builtin_amdgcn_sched_barrier(0)
; #define WAIT_BAR(N) asm volatile("s_waitcnt vmcnt(" #N ") lgkmcnt(0)\n\ts_barrier":::"memory")
; __device__ __forceinline__ s16x4 vtr(lds_cptr p){ return __builtin_bit_cast(s16x4,__builtin_amdgcn_ds_read_tr16_b64_v4i16((__attribute__((address_space(3))) v4i16_t*)p)); }
;   #define ROT3() do{ const int x_=c0; c0=c1; c1=c2; c2=x_; }while(0)
;   #define PKW(P,B) cvtpk_s(P[B],P[B+1])
; template<int THRL> __device__ __forceinline__ void attn_unit(int qb,const bf16*Q,const bf16*__restrict__ K,const bf16*__restrict__ V,bf16*O,char*shm){
;     ...
;     #pragma unroll
;     for(int r=0;r<16;++r){C0[r]=__builtin_amdgcn_exp2f(C0[r]);C1[r]=__builtin_amdgcn_exp2f(C1[r]);}
;     { float s0=C0[0]+C0[1],s1=C1[0]+C1[1];
;       #pragma unroll
;       for(int r=2;r<16;++r){s0+=C0[r];s1+=C1[r];}
;       l_reg+=s0+s1; }
;     const u32x4 pw0=(u32x4){PKW(C0,0),PKW(C0,2),PKW(C0,4),PKW(C0,6)},pw1=(u32x4){PKW(C0,8),PKW(C0,10),PKW(C0,12),PKW(C0,14)},pw2=(u32x4){PKW(C1,0),PKW(C1,2),PKW(C1,4),PKW(C1,6)},pw3=(u32x4){PKW(C1,8),PKW(C1,10),PKW(C1,12),PKW(C1,14)};
;     SBAR();
;     ...
;     s16x4 w2l_[4],w2h_[4],w3l_[4],w3h_[4];
;     #pragma unroll
;     for(int d_=0;d_<4;++d_){ w2l_[d_]=vtr(vp_+(d_*4096+2*1024)); w2h_[d_]=vtr(vp_+(d_*4096+2*1024+512)); }
;     SBAR();
;     #pragma unroll
;     for(int d_=0;d_<4;++d_){ o[d_]=__builtin_amdgcn_mfma_f32_32x32x16_bf16(__builtin_bit_cast(bf16x8,pw0),VFRAG(vl_,vh_,d_*2),o[d_],0,0,0); }
;     SBAR();
;     #pragma unroll
;     for(int d_=0;d_<4;++d_){ w3l_[d_]=vtr(vp_+(d_*4096+3*1024)); w3h_[d_]=vtr(vp_+(d_*4096+3*1024+512)); }
;     SBAR();
;     #pragma unroll
;     for(int d_=0;d_<4;++d_){ o[d_]=__builtin_amdgcn_mfma_f32_32x32x16_bf16(__builtin_bit_cast(bf16x8,pw1),VFRAG(vl_,vh_,d_*2+1),o[d_],0,0,0); }
;     #pragma unroll
;     for(int d_=0;d_<4;++d_){ o[d_]=__builtin_amdgcn_mfma_f32_32x32x16_bf16(__builtin_bit_cast(bf16x8,pw2),VFRAG(w2l_,w2h_,d_),o[d_],0,0,0); }
;     #pragma unroll
;     for(int d_=0;d_<4;++d_){ o[d_]=__builtin_amdgcn_mfma_f32_32x32x16_bf16(__builtin_bit_cast(bf16x8,pw3),VFRAG(w3l_,w3h_,d_),o[d_],0,0,0); }
;     SBAR();
;     ...
;     if(t+2<NT){WAIT_BAR(3);}else{WAIT_BAR(0);}
;     ROT3();
.LBB0_372:
	v_exp_f32_e32 v80, v80
	v_exp_f32_e32 v81, v81
	v_exp_f32_e32 v82, v82
	v_exp_f32_e32 v83, v83
	v_exp_f32_e32 v84, v84
	v_exp_f32_e32 v85, v85
	v_exp_f32_e32 v86, v86
	v_exp_f32_e32 v87, v87
	ds_read_b64_tr_b16 v[210:211], v193 offset:26624
	ds_read_b64_tr_b16 v[212:213], v193 offset:27136
	ds_read_b64_tr_b16 v[214:215], v193 offset:30720
	ds_read_b64_tr_b16 v[216:217], v193 offset:31232
	ds_read_b64_tr_b16 v[218:219], v193 offset:34816
	ds_read_b64_tr_b16 v[220:221], v193 offset:35328
	ds_read_b64_tr_b16 v[232:233], v193 offset:38912
	ds_read_b64_tr_b16 v[234:235], v193 offset:39424
	v_cvt_pk_bf16_f32 v194, v80, v81
	v_cvt_pk_bf16_f32 v195, v82, v83
	v_cvt_pk_bf16_f32 v196, v84, v85
	v_cvt_pk_bf16_f32 v197, v86, v87
	s_and_b64 vcc, exec, s[12:13]
	v_exp_f32_e32 v88, v88
	v_exp_f32_e32 v89, v89
	v_mfma_f32_32x32x16_bf16 v[48:63], v[194:197], v[156:159], v[48:63]
	v_exp_f32_e32 v90, v90
	v_exp_f32_e32 v91, v91
	v_cvt_pk_bf16_f32 v198, v88, v89
	s_waitcnt lgkmcnt(14)
	v_mfma_f32_32x32x16_bf16 v[32:47], v[194:197], v[152:155], v[32:47]
	v_exp_f32_e32 v92, v92
	v_exp_f32_e32 v93, v93
	v_cvt_pk_bf16_f32 v199, v90, v91
	s_cbranch_vccnz .Lattn_nodma0
	s_lshl_b32 s14, s29, 13
	s_add_i32 s14, s14, s9
	s_mov_b32 m0, s14
	s_nop 0
	global_load_lds_dwordx4 v[182:183], off
.Lattn_nodma0:
	v_mfma_f32_32x32x16_bf16 v[16:31], v[194:197], v[148:151], v[16:31]
	v_exp_f32_e32 v94, v94
	v_exp_f32_e32 v95, v95
	v_cvt_pk_bf16_f32 v200, v92, v93
	s_waitcnt lgkmcnt(10)
	v_mfma_f32_32x32x16_bf16 v[0:15], v[194:197], v[144:147], v[0:15]
	ds_read_b64_tr_b16 v[144:145], v193 offset:27648
	ds_read_b64_tr_b16 v[146:147], v193 offset:28160
	ds_read_b64_tr_b16 v[148:149], v193 offset:31744
	ds_read_b64_tr_b16 v[150:151], v193 offset:32256
	ds_read_b64_tr_b16 v[152:153], v193 offset:35840
	ds_read_b64_tr_b16 v[154:155], v193 offset:36352
	ds_read_b64_tr_b16 v[156:157], v193 offset:39936
	ds_read_b64_tr_b16 v[158:159], v193 offset:40448
	v_cvt_pk_bf16_f32 v201, v94, v95
	v_exp_f32_e32 v96, v96
	v_exp_f32_e32 v97, v97
	v_mfma_f32_32x32x16_bf16 v[48:63], v[198:201], v[140:143], v[48:63]
	v_exp_f32_e32 v98, v98
	v_exp_f32_e32 v99, v99
	v_cvt_pk_bf16_f32 v202, v96, v97
	v_add_f32_e32 v80, v80, v81
	v_mfma_f32_32x32x16_bf16 v[32:47], v[198:201], v[136:139], v[32:47]
	v_exp_f32_e32 v100, v100
	v_exp_f32_e32 v101, v101
	v_cvt_pk_bf16_f32 v203, v98, v99
	v_add_f32_e32 v80, v82, v80
	s_cbranch_vccnz .Lattn_nodma1
	s_lshl_b32 s14, s29, 14
	s_add_i32 s14, s14, s11
	s_mov_b32 m0, s14
	v_lshl_add_u64 v[162:163], v[180:181], 0, s[50:51]
	global_load_lds_dwordx4 v[180:181], off
.Lattn_nodma1:
	v_mfma_f32_32x32x16_bf16 v[16:31], v[198:201], v[132:135], v[16:31]
	v_exp_f32_e32 v102, v102
	v_exp_f32_e32 v103, v103
	v_cvt_pk_bf16_f32 v204, v100, v101
	v_add_f32_e32 v80, v83, v80
	s_waitcnt lgkmcnt(14)
	v_mfma_f32_32x32x16_bf16 v[0:15], v[198:201], v[128:131], v[0:15]
	v_cvt_pk_bf16_f32 v205, v102, v103
	v_exp_f32_e32 v104, v104
	v_exp_f32_e32 v105, v105
	v_add_f32_e32 v80, v84, v80
	v_mfma_f32_32x32x16_bf16 v[48:63], v[202:205], v[210:213], v[48:63]
	v_exp_f32_e32 v106, v106
	v_exp_f32_e32 v107, v107
	v_cvt_pk_bf16_f32 v206, v104, v105
	v_add_f32_e32 v80, v85, v80
	s_waitcnt lgkmcnt(12)
	v_mfma_f32_32x32x16_bf16 v[32:47], v[202:205], v[214:217], v[32:47]
	s_cbranch_vccnz .Lattn_nodma2
	s_addk_i32 s14, 0x2000
	s_mov_b32 m0, s14
	s_nop 0
	global_load_lds_dwordx4 v[162:163], off
.Lattn_nodma2:
	v_exp_f32_e32 v108, v108
	v_exp_f32_e32 v109, v109
	v_cvt_pk_bf16_f32 v207, v106, v107
	v_add_f32_e32 v80, v86, v80
	s_waitcnt lgkmcnt(10)
	v_mfma_f32_32x32x16_bf16 v[16:31], v[202:205], v[218:221], v[16:31]
	v_exp_f32_e32 v110, v110
	v_exp_f32_e32 v111, v111
	v_cvt_pk_bf16_f32 v208, v108, v109
	v_add_f32_e32 v80, v87, v80
	s_waitcnt lgkmcnt(8)
	v_mfma_f32_32x32x16_bf16 v[0:15], v[202:205], v[232:235], v[0:15]
	v_cvt_pk_bf16_f32 v209, v110, v111
	v_add_f32_e32 v81, v96, v97
	v_add_f32_e32 v80, v88, v80
	v_add_f32_e32 v81, v98, v81
	v_add_u32_e32 v192, 64, v192
	v_lshl_add_u64 v[180:181], v[180:181], 0, s[88:89]
	v_lshl_add_u64 v[182:183], v[182:183], 0, s[88:89]
	s_waitcnt lgkmcnt(6)
	v_mfma_f32_32x32x16_bf16 v[48:63], v[206:209], v[144:147], v[48:63]
	v_add_f32_e32 v80, v89, v80
	v_add_f32_e32 v81, v99, v81
	v_add_f32_e32 v80, v90, v80
	v_add_f32_e32 v81, v100, v81
	v_add_f32_e32 v80, v91, v80
	v_add_f32_e32 v81, v101, v81
	s_waitcnt lgkmcnt(4)
	v_mfma_f32_32x32x16_bf16 v[32:47], v[206:209], v[148:151], v[32:47]
	v_add_f32_e32 v80, v92, v80
	v_add_f32_e32 v81, v102, v81
	v_add_f32_e32 v80, v93, v80
	v_add_f32_e32 v81, v103, v81
	v_add_f32_e32 v80, v94, v80
	v_add_f32_e32 v81, v104, v81
	s_waitcnt lgkmcnt(2)
	v_mfma_f32_32x32x16_bf16 v[16:31], v[206:209], v[152:155], v[16:31]
	v_add_f32_e32 v80, v95, v80
	v_add_f32_e32 v81, v105, v81
	v_add_f32_e32 v81, v106, v81
	v_add_f32_e32 v81, v107, v81
	v_add_f32_e32 v81, v108, v81
	v_add_f32_e32 v81, v109, v81
	s_waitcnt lgkmcnt(0)
	v_mfma_f32_32x32x16_bf16 v[0:15], v[206:209], v[156:159], v[0:15]
	v_add_f32_e32 v81, v110, v81
	v_add_f32_e32 v81, v111, v81
	v_add_f32_e32 v80, v81, v80
	v_add_f32_e32 v179, v179, v80
	s_and_b64 vcc, exec, s[12:13]
	s_add_i32 s31, s31, 1
	s_mov_b32 s35, s27
	s_mov_b32 s27, s29
	s_mov_b32 s29, s34
	s_mov_b32 s34, s35
	s_add_i32 s12, s31, 2
	s_cmp_ge_i32 s12, s26
	s_cselect_b64 s[12:13], -1, 0
	s_add_i32 s14, s28, s31
	s_cbranch_vccnz .Lattn_tailbar
	s_waitcnt vmcnt(3) lgkmcnt(0)
	s_barrier
	s_cmp_eq_u32 s14, 0
	s_cbranch_scc0 .Lattn_top
	s_branch .LBB0_379
.Lattn_tailbar:
	s_waitcnt vmcnt(0) lgkmcnt(0)
	s_barrier
	s_cmp_eq_u32 s14, 0
	s_cbranch_scc0 .Lattn_top
	s_branch .LBB0_379
